# phase-0 weight copy loop keeps two tiles of loads in flight (second register set, copied after the LDS write)
# baseline (speedup 1.0000x reference)
.LBB0_566:
	v_readlane_b32 s8, v254, 15
	v_readlane_b32 s9, v254, 16
	v_readlane_b32 s10, v254, 17
	v_readlane_b32 s11, v254, 18
	v_readlane_b32 s12, v254, 19
	v_readlane_b32 s13, v254, 20
	v_readlane_b32 s14, v254, 21
	v_readlane_b32 s15, v254, 22
	v_readlane_b32 s16, v254, 23
	v_readlane_b32 s17, v254, 24
	v_readlane_b32 s18, v254, 25
	v_readlane_b32 s19, v254, 26
	v_readlane_b32 s20, v254, 27
	v_readlane_b32 s21, v254, 28
	v_readlane_b32 s22, v254, 29
	v_readlane_b32 s23, v254, 30
	s_mov_b64 s[6:7], s[8:9]
	s_mov_b64 s[4:5], s[14:15]
	s_mov_b64 s[0:1], s[10:11]
	s_mov_b64 s[2:3], s[12:13]
	v_readlane_b32 s8, v254, 31
	v_readlane_b32 s9, v254, 32
	v_readlane_b32 s10, v254, 33
	v_readlane_b32 s11, v254, 34
	v_readlane_b32 s12, v254, 35
	v_readlane_b32 s13, v254, 36
	v_readlane_b32 s14, v254, 37
	v_readlane_b32 s15, v254, 38
	v_readlane_b32 s22, v254, 45
	v_readlane_b32 s23, v254, 46
	s_mov_b64 s[2:3], s[22:23]
	v_readlane_b32 s8, v252, 0
	v_readlane_b32 s9, v252, 1
	s_mov_b64 s[2:3], s[8:9]
	v_readlane_b32 s10, v252, 2
	v_readlane_b32 s11, v252, 3
	s_mov_b64 s[2:3], s[10:11]
	v_readlane_b32 s8, v253, 41
	v_readlane_b32 s9, v253, 42
	s_mov_b32 s2, s62
	s_andn2_b64 vcc, exec, s[8:9]
	v_readlane_b32 s16, v254, 39
	v_readlane_b32 s17, v254, 40
	v_readlane_b32 s18, v254, 41
	v_readlane_b32 s19, v254, 42
	v_readlane_b32 s20, v254, 43
	v_readlane_b32 s21, v254, 44
	v_readlane_b32 s12, v252, 4
	v_readlane_b32 s13, v252, 5
	v_readlane_b32 s14, v252, 6
	v_readlane_b32 s15, v252, 7
	s_cbranch_vccnz .LBB0_573
	s_waitcnt vmcnt(0)
	v_mov_b32_e32 v0, v186
	v_readlane_b32 s8, v254, 59
	s_mul_hi_i32 s3, s8, 0x2a30000
	s_mul_i32 s8, s8, 0x2a30000
	s_waitcnt lgkmcnt(0)
	v_ashrrev_i32_e32 v1, 5, v0
	v_lshlrev_b32_e32 v0, 2, v0
	s_add_u32 s8, s0, s8
	v_and_b32_e32 v0, 0x7c, v0
	v_readlane_b32 s0, v253, 43
	v_readlane_b32 s9, v254, 60
	s_addc_u32 s9, s1, s3
	v_or_b32_e32 v0, s0, v0
	v_cmp_gt_i32_e64 s[10:11], s77, v0
	v_readlane_b32 s0, v253, 44
	v_mov_b64_e32 v[2:3], s[8:9]
	v_cndmask_b32_e64 v0, 0, v0, s[10:11]
	v_add_u32_e32 v1, s0, v1
	s_movk_i32 s0, 0x5460
	v_mad_i64_i32 v[2:3], s[0:1], v1, s0, v[2:3]
	v_ashrrev_i32_e32 v1, 31, v0
	v_lshl_add_u64 v[8:9], v[0:1], 2, v[2:3]
	s_mov_b32 s0, 0x54000
	v_add_co_u32_e32 v4, vcc, s0, v8
	s_mov_b32 s0, 0xa8000
	s_nop 0
	v_addc_co_u32_e32 v5, vcc, 0, v9, vcc
	v_add_co_u32_e32 v10, vcc, s0, v8
	global_load_dwordx4 v[0:3], v[8:9], off
	s_nop 0
	global_load_dwordx4 v[4:7], v[4:5], off offset:1536
	v_addc_co_u32_e32 v11, vcc, 0, v9, vcc
	v_add_co_u32_e32 v12, vcc, s92, v8
	s_lshl_b32 s3, s2, 7
	s_nop 0
	v_addc_co_u32_e32 v13, vcc, 0, v9, vcc
	global_load_dwordx4 v[8:11], v[10:11], off offset:3072
	s_nop 0
	global_load_dwordx4 v[12:15], v[12:13], off offset:512
	v_readlane_b32 s14, v253, 59
	s_mov_b32 s15, s84
	s_add_i32 s16, s15, s2
	s_add_i32 s17, s14, s3
	s_mul_hi_i32 s0, s16, 0x2e8ba2e9
	v_mov_b32_e32 v50, v186
	s_lshr_b32 s1, s0, 31
	s_ashr_i32 s0, s0, 3
	s_add_i32 s0, s0, s1
	v_ashrrev_i32_e32 v51, 5, v50
	v_lshlrev_b32_e32 v50, 2, v50
	v_and_b32_e32 v50, 0x7c, v50
	s_mul_i32 s1, s0, 0x1600
	v_subrev_u32_e32 v50, s1, v50
	v_add_u32_e32 v50, s17, v50
	v_cmp_gt_i32_e32 vcc, s77, v50
	v_lshl_add_u32 v51, s0, 6, v51
	v_mov_b64_e32 v[52:53], s[8:9]
	v_cndmask_b32_e32 v50, 0, v50, vcc
	s_movk_i32 s0, 0x5460
	v_mad_i64_i32 v[52:53], s[0:1], v51, s0, v[52:53]
	v_ashrrev_i32_e32 v51, 31, v50
	v_lshl_add_u64 v[58:59], v[50:51], 2, v[52:53]
	s_mov_b32 s0, 0x54000
	v_add_co_u32_e64 v54, s[0:1], s0, v58
	s_nop 1
	v_addc_co_u32_e64 v55, s[0:1], 0, v59, s[0:1]
	s_mov_b32 s0, 0xa8000
	s_nop 0
	v_add_co_u32_e64 v60, s[0:1], s0, v58
	global_load_dwordx4 v[34:37], v[58:59], off
	s_nop 0
	global_load_dwordx4 v[38:41], v[54:55], off offset:1536
	v_addc_co_u32_e64 v61, s[0:1], 0, v59, s[0:1]
	v_add_co_u32_e64 v62, s[0:1], s92, v58
	s_nop 1
	v_addc_co_u32_e64 v63, s[0:1], 0, v59, s[0:1]
	global_load_dwordx4 v[42:45], v[60:61], off offset:3072
	s_nop 0
	global_load_dwordx4 v[46:49], v[62:63], off offset:512
	s_mov_b64 s[18:19], vcc
	s_waitcnt vmcnt(4)
.Lpw_loop:
	v_mov_b32_e32 v16, v186
	v_cndmask_b32_e64 v19, 0, v3, s[10:11]
	v_ashrrev_i32_e32 v20, 5, v16
	v_lshlrev_b32_e32 v16, 4, v16
	v_and_b32_e32 v21, 0x1f0, v16
	v_mul_lo_u32 v20, v20, s87
	v_cndmask_b32_e64 v18, 0, v2, s[10:11]
	v_cndmask_b32_e64 v17, 0, v1, s[10:11]
	v_cndmask_b32_e64 v16, 0, v0, s[10:11]
	v_add3_u32 v20, 0, v21, v20
	ds_write_b128 v20, v[16:19]
	v_cndmask_b32_e64 v19, 0, v7, s[10:11]
	v_cndmask_b32_e64 v18, 0, v6, s[10:11]
	v_cndmask_b32_e64 v17, 0, v5, s[10:11]
	v_cndmask_b32_e64 v16, 0, v4, s[10:11]
	ds_write_b128 v20, v[16:19] offset:8448
	v_cndmask_b32_e64 v19, 0, v11, s[10:11]
	v_cndmask_b32_e64 v18, 0, v10, s[10:11]
	v_cndmask_b32_e64 v17, 0, v9, s[10:11]
	v_cndmask_b32_e64 v16, 0, v8, s[10:11]
	ds_write_b128 v20, v[16:19] offset:16896
	v_cndmask_b32_e64 v19, 0, v15, s[10:11]
	v_cndmask_b32_e64 v18, 0, v14, s[10:11]
	v_cndmask_b32_e64 v17, 0, v13, s[10:11]
	v_cndmask_b32_e64 v16, 0, v12, s[10:11]
	ds_write_b128 v20, v[16:19] offset:25344
	s_waitcnt lgkmcnt(0)
	s_barrier
	s_add_i32 s16, s15, s2
	s_cmpk_lt_i32 s16, 0x580
	s_cbranch_scc0 .Lpw_nonext
	s_waitcnt vmcnt(0)
	v_mov_b32_e32 v0, v34
	v_mov_b32_e32 v1, v35
	v_mov_b32_e32 v2, v36
	v_mov_b32_e32 v3, v37
	v_mov_b32_e32 v4, v38
	v_mov_b32_e32 v5, v39
	v_mov_b32_e32 v6, v40
	v_mov_b32_e32 v7, v41
	v_mov_b32_e32 v8, v42
	v_mov_b32_e32 v9, v43
	v_mov_b32_e32 v10, v44
	v_mov_b32_e32 v11, v45
	v_mov_b32_e32 v12, v46
	v_mov_b32_e32 v13, v47
	v_mov_b32_e32 v14, v48
	v_mov_b32_e32 v15, v49
	s_mov_b64 s[10:11], s[18:19]
	s_add_i32 s17, s16, s2
	s_cmpk_lt_i32 s17, 0x580
	s_cbranch_scc0 .Lpw_nonext
	s_add_i32 s19, s14, s3
	s_add_i32 s19, s19, s3
	s_mul_hi_i32 s0, s17, 0x2e8ba2e9
	v_mov_b32_e32 v50, v186
	s_lshr_b32 s1, s0, 31
	s_ashr_i32 s0, s0, 3
	s_add_i32 s0, s0, s1
	v_ashrrev_i32_e32 v51, 5, v50
	v_lshlrev_b32_e32 v50, 2, v50
	v_and_b32_e32 v50, 0x7c, v50
	s_mul_i32 s1, s0, 0x1600
	v_subrev_u32_e32 v50, s1, v50
	v_add_u32_e32 v50, s19, v50
	v_cmp_gt_i32_e32 vcc, s77, v50
	v_lshl_add_u32 v51, s0, 6, v51
	v_mov_b64_e32 v[52:53], s[8:9]
	v_cndmask_b32_e32 v50, 0, v50, vcc
	s_movk_i32 s0, 0x5460
	v_mad_i64_i32 v[52:53], s[0:1], v51, s0, v[52:53]
	v_ashrrev_i32_e32 v51, 31, v50
	v_lshl_add_u64 v[58:59], v[50:51], 2, v[52:53]
	s_mov_b32 s0, 0x54000
	v_add_co_u32_e64 v54, s[0:1], s0, v58
	s_nop 1
	v_addc_co_u32_e64 v55, s[0:1], 0, v59, s[0:1]
	s_mov_b32 s0, 0xa8000
	s_nop 0
	v_add_co_u32_e64 v60, s[0:1], s0, v58
	global_load_dwordx4 v[34:37], v[58:59], off
	s_nop 0
	global_load_dwordx4 v[38:41], v[54:55], off offset:1536
	v_addc_co_u32_e64 v61, s[0:1], 0, v59, s[0:1]
	v_add_co_u32_e64 v62, s[0:1], s92, v58
	s_nop 1
	v_addc_co_u32_e64 v63, s[0:1], 0, v59, s[0:1]
	global_load_dwordx4 v[42:45], v[60:61], off offset:3072
	s_nop 0
	global_load_dwordx4 v[46:49], v[62:63], off offset:512
	s_mov_b64 s[18:19], vcc
.Lpw_nonext:
	s_mul_hi_i32 s0, s15, 0x2e8ba2e9
	v_mov_b32_e32 v16, v186
	s_lshr_b32 s1, s0, 31
	s_ashr_i32 s0, s0, 3
	s_add_i32 s0, s0, s1
	v_lshlrev_b32_e32 v18, 4, v16
	v_and_b32_e32 v18, 48, v18
	v_ashrrev_i32_e32 v17, 2, v16
	v_and_b32_e32 v16, -4, v16
	v_mul_u32_u24_e32 v19, 0x210, v18
	s_mul_i32 s1, s0, 0x1600
	v_add3_u32 v32, 0, v16, v19
	v_subrev_u32_e32 v16, s1, v17
	v_add_u32_e32 v16, s14, v16
	v_ashrrev_i32_e32 v17, 31, v16
	v_lshlrev_b64 v[16:17], 12, v[16:17]
	s_lshl_b32 s0, s0, 6
	v_lshl_add_u64 v[16:17], s[54:55], 0, v[16:17]
	s_ashr_i32 s1, s0, 31
	v_lshl_add_u64 v[16:17], s[0:1], 1, v[16:17]
	v_lshlrev_b32_e32 v64, 1, v18
	v_add_u32_e32 v18, 0x400, v32
	v_lshl_add_u64 v[20:21], v[16:17], 0, v[64:65]
	ds_read2_b32 v[16:17], v32 offset1:132
	ds_read2_b32 v[18:19], v18 offset0:8 offset1:140
	v_add_u32_e32 v22, 0x800, v32
	v_add_u32_e32 v24, 0xc00, v32
	v_add_u32_e32 v26, 0x1000, v32
	v_add_u32_e32 v28, 0x1400, v32
	v_add_u32_e32 v30, 0x1800, v32
	v_add_u32_e32 v32, 0x1c00, v32
	ds_read2_b32 v[22:23], v22 offset0:16 offset1:148
	ds_read2_b32 v[24:25], v24 offset0:24 offset1:156
	ds_read2_b32 v[26:27], v26 offset0:32 offset1:164
	ds_read2_b32 v[28:29], v28 offset0:40 offset1:172
	ds_read2_b32 v[30:31], v30 offset0:48 offset1:180
	ds_read2_b32 v[32:33], v32 offset0:56 offset1:188
	s_waitcnt lgkmcnt(7)
	v_cvt_pk_bf16_f32 v16, v16, v17
	s_waitcnt lgkmcnt(6)
	v_cvt_pk_bf16_f32 v17, v18, v19
	s_waitcnt lgkmcnt(5)
	v_cvt_pk_bf16_f32 v18, v22, v23
	s_waitcnt lgkmcnt(4)
	v_cvt_pk_bf16_f32 v19, v24, v25
	global_store_dwordx4 v[20:21], v[16:19], off
	s_waitcnt lgkmcnt(3)
	s_nop 0
	v_cvt_pk_bf16_f32 v16, v26, v27
	s_waitcnt lgkmcnt(2)
	v_cvt_pk_bf16_f32 v17, v28, v29
	s_waitcnt lgkmcnt(1)
	v_cvt_pk_bf16_f32 v18, v30, v31
	s_waitcnt lgkmcnt(0)
	v_cvt_pk_bf16_f32 v19, v32, v33
	global_store_dwordx4 v[20:21], v[16:19], off offset:16
	s_barrier
	s_add_i32 s14, s14, s3
	s_mov_b32 s15, s16
	s_cmpk_lt_i32 s15, 0x580
	s_cbranch_scc1 .Lpw_loop
	s_branch .LBB0_573
